# mode D second half: next-tile address computation moved from the loop latch into the MFMA-to-VALU hazard gap (replaces s_nop 9)
# speedup vs baseline: 1.0021x; 1.0021x over previous
; template <int MODE>
; DI void attn_tile(const Params& p, int layer, int tile, char* smem) {
;     ...
;     lstore(rk0, rv0, 1);
;     gload(rk0, rv0, kt0 + j + 3);
;     __syncthreads();
;     if (j + 1 >= ntile) break;
;     compute(1, kt0 + j + 1);
;     lstore(rk1, rv1, 0);
;     gload(rk1, rv1, kt0 + j + 4);
;     __syncthreads();
;   }
.LBB0_115:
	s_or_b64 exec, exec, s[0:1]
	v_mov_b32_e32 v212, v0
	global_load_dwordx4 v[138:141], v[248:249], off
	global_load_dwordx4 v[142:145], v[250:251], off
	s_waitcnt vmcnt(5)
	ds_write_b128 v190, v[134:137] offset:26624
	global_load_dwordx4 v[134:137], v[204:205], off
	s_cmp_lt_u32 s21, 62
	s_waitcnt lgkmcnt(0)
	s_barrier
	s_cbranch_scc0 .LBB0_129

; DI f32x16 mfma(bf16x8 a, bf16x8 b, f32x16 c) { return __builtin_amdgcn_mfma_f32_32x32x16_bf16(a, b, c, 0, 0, 0); }
; template <int MODE>
; DI void attn_tile(const Params& p, int layer, int tile, char* smem) {
;     ...
;       f32x16 s0 = negm, s1 = negm;
; #pragma unroll
;       for (int d0 = 0; d0 < NKQ; ++d0) {
;         bf16x8 k0 = *(const bf16x8*)(Kb + d0 * 16);
;         bf16x8 k1 = *(const bf16x8*)(Kb + 32 * KROW + d0 * 16);
;         s0 = mfma(k0, qf[d0], s0);
;         s1 = mfma(k1, qf[d0], s1);
;       }
;       if (MODE == 0) {
;         const float* tb = tbl + (kt * 64 + 4 * h - qpos + 1280);
; #pragma unroll
;         for (int i = 0; i < 16; ++i) { s0[i] += tb[(i & 3) + 8 * (i >> 2)]; s1[i] += tb[32 + (i & 3) + 8 * (i >> 2)]; }
;       }
;       if (MODE == 2) {
;         const float* tb = tbl + (kt - qr + 7) * 31 + (15 - qc);
; #pragma unroll
;         for (int i = 0; i < 16; ++i) {
;           const int kc0 = 4 * h + (i & 3) + 8 * (i >> 2), kc1 = kc0 + 32;
;           const bool v0 = (kc0 >= cs) && (kc0 < cs + 16), v1 = (kc1 >= cs) && (kc1 < cs + 16);
;           const float b0 = tb[v0 ? kc0 : qc], b1 = tb[v1 ? kc1 : qc];
;           s0[i] = v0 ? s0[i] + b0 : NEGBIG;
;           s1[i] = v1 ? s1[i] + b1 : NEGBIG;
;         }
;       }
;       float ma = __builtin_fmaxf(__builtin_fmaxf(s0[0], s0[1]), s0[2]), mb = __builtin_fmaxf(__builtin_fmaxf(s1[0], s1[1]), s1[2]);
; #pragma unroll
;       for (int i = 3; i < 15; i += 2) { ma = __builtin_fmaxf(__builtin_fmaxf(ma, s0[i]), s0[i + 1]); mb = __builtin_fmaxf(__builtin_fmaxf(mb, s1[i]), s1[i + 1]); }
;       float mt = __builtin_fmaxf(__builtin_fmaxf(ma, s0[15]), s1[15]);
;       mt = hmax(__builtin_fmaxf(mt, mb));
.LBB0_123:
	s_or_b64 exec, exec, s[0:1]
	s_waitcnt vmcnt(3)
	ds_write_b128 v190, v[114:117] offset:35840
	global_load_dwordx4 v[122:125], v[248:249], off
	global_load_dwordx4 v[118:121], v[250:251], off
	global_load_dwordx4 v[114:117], v[204:205], off
	s_waitcnt lgkmcnt(0)
	s_barrier
	ds_read_b128 v[94:97], v192 offset:13312
	ds_read_b128 v[146:149], v192 offset:13376
	s_waitcnt lgkmcnt(1)
	v_mfma_f32_32x32x16_bf16 v[66:81], v[94:97], v[98:101], v[34:49]
	ds_read_b128 v[94:97], v192 offset:19968
	v_add_f32_e32 v0, v224, v217
	v_add_f32_e32 v0, 0, v0
	v_add_f32_e32 v93, v229, v225
	v_add_f32_e32 v0, v93, v0
	v_add_f32_e32 v93, v218, v215
	v_add_f32_e32 v0, v93, v0
	s_waitcnt lgkmcnt(0)
	v_mfma_f32_32x32x16_bf16 v[50:65], v[94:97], v[98:101], v[34:49]
	ds_read_b128 v[94:97], v192 offset:13344
	v_add_f32_e32 v93, v232, v230
	v_add_f32_e32 v0, v93, v0
	v_add_f32_e32 v93, v214, v213
	v_add_f32_e32 v0, v93, v0
	v_add_f32_e32 v93, v219, v216
	v_add_f32_e32 v0, v93, v0
	s_waitcnt lgkmcnt(0)
	v_mfma_f32_32x32x16_bf16 v[66:81], v[94:97], v[102:105], v[66:81]
	ds_read_b128 v[94:97], v192 offset:20000
	v_add_f32_e32 v93, v233, v231
	v_add_f32_e32 v0, v93, v0
	v_add_f32_e32 v93, v226, v220
	v_add_f32_e32 v0, v93, v0
	v_add_f32_e32 v93, v227, v221
	v_add_f32_e32 v0, v93, v0
	s_waitcnt lgkmcnt(0)
	v_mfma_f32_32x32x16_bf16 v[50:65], v[94:97], v[102:105], v[50:65]
	ds_read_b128 v[94:97], v192 offset:20032
	ds_read_b128 v[150:153], v192 offset:13408
	v_add_f32_e32 v93, v228, v222
	v_add_f32_e32 v0, v93, v0
	v_add_f32_e32 v92, v92, v223
	v_add_f32_e32 v0, v92, v0
	v_add_f32_e32 v88, v90, v88
	v_add_f32_e32 v0, v88, v0
	v_mfma_f32_32x32x16_bf16 v[66:81], v[146:149], v[106:109], v[66:81]
	ds_read_b128 v[146:149], v192 offset:20064
	v_add_f32_e32 v88, v91, v89
	v_add_f32_e32 v0, v88, v0
	ds_read_b128 v[88:91], v192 offset:13440
	v_add_f32_e32 v86, v87, v86
	v_add_f32_e32 v0, v86, v0
	v_add_f32_e32 v82, v84, v82
	s_waitcnt lgkmcnt(3)
	v_mfma_f32_32x32x16_bf16 v[50:65], v[94:97], v[106:109], v[50:65]
	v_add_f32_e32 v0, v82, v0
	v_add_f32_e32 v86, v85, v83
	ds_read_b128 v[82:85], v192 offset:20096
	ds_read_b128 v[162:165], v192 offset:13472
	v_add_f32_e32 v0, v86, v0
	v_add_f32_e32 v0, v212, v0
	s_waitcnt lgkmcnt(4)
	v_mfma_f32_32x32x16_bf16 v[66:81], v[150:153], v[110:113], v[66:81]
	ds_read_b64_tr_b16 v[158:159], v191 offset:35840
	ds_read_b64_tr_b16 v[160:161], v191 offset:36992
	ds_read_b64_tr_b16 v[156:157], v191 offset:37056
	ds_read_b64_tr_b16 v[154:155], v191 offset:35904
	ds_read_b128 v[166:169], v192 offset:20128
	ds_read_b64_tr_b16 v[150:151], v191 offset:38144
	s_waitcnt lgkmcnt(9)
	v_mfma_f32_32x32x16_bf16 v[50:65], v[146:149], v[110:113], v[50:65]
	s_waitcnt lgkmcnt(8)
	v_mfma_f32_32x32x16_bf16 v[66:81], v[88:91], v[126:129], v[66:81]
	ds_read_b64_tr_b16 v[152:153], v191 offset:39296
	ds_read_b64_tr_b16 v[148:149], v191 offset:39360
	ds_read_b64_tr_b16 v[146:147], v191 offset:38208
	ds_read_b64_tr_b16 v[94:95], v191 offset:40448
	ds_read_b64_tr_b16 v[96:97], v191 offset:41600
	ds_read_b64_tr_b16 v[92:93], v191 offset:41664
	ds_read_b64_tr_b16 v[90:91], v191 offset:40512
	s_waitcnt lgkmcnt(14)
	v_mfma_f32_32x32x16_bf16 v[50:65], v[82:85], v[126:129], v[50:65]
	ds_read_b64_tr_b16 v[82:83], v191 offset:42752
	ds_read_b64_tr_b16 v[84:85], v191 offset:43904
	ds_read_b64_tr_b16 v[88:89], v191 offset:43968
	ds_read_b64_tr_b16 v[86:87], v191 offset:42816
	s_waitcnt lgkmcnt(14)
	v_mfma_f32_32x32x16_bf16 v[66:81], v[162:165], v[130:133], v[66:81]
	s_waitcnt lgkmcnt(12)
	v_mfma_f32_32x32x16_bf16 v[50:65], v[166:169], v[130:133], v[50:65]
	s_min_u32 s0, s21, 59
	s_lshl_b32 s0, s0, 6
	s_addk_i32 s0, 0x100
	s_mul_i32 s1, s0, 0x180
	v_mov_b32_e32 v209, 0
	v_add_u32_e32 v208, s1, v182
	v_lshl_add_u64 v[248:249], v[208:209], 1, s[14:15]
	v_add_u32_e32 v208, s1, v184
	v_lshl_add_u64 v[250:251], v[208:209], 1, s[14:15]
	v_lshl_add_u32 v208, s0, 8, v186
	v_lshl_add_u64 v[204:205], v[208:209], 1, s[16:17]
	v_max_f32_e32 v162, v67, v67
	v_max_f32_e32 v163, v66, v66
	v_max_f32_e32 v162, v163, v162
	v_max3_f32 v162, v162, v68, v69
	v_max3_f32 v162, v162, v70, v71
	v_max3_f32 v162, v162, v72, v73
	v_max3_f32 v162, v162, v74, v75
	v_max3_f32 v163, v50, v51, v52
	v_max3_f32 v163, v163, v53, v54
	v_max3_f32 v163, v163, v55, v56
	v_max3_f32 v163, v163, v57, v58
	v_max3_f32 v163, v163, v59, v60
	v_max3_f32 v162, v162, v76, v77
	v_max3_f32 v163, v163, v61, v62
	v_max3_f32 v162, v162, v78, v79
	v_max3_f32 v163, v163, v63, v64
	v_max3_f32 v162, v162, v80, v81
	v_max3_f32 v162, v162, v65, v163
	v_mov_b32_e32 v163, v162
	s_nop 1
	v_permlane32_swap_b32_e32 v162, v163
	v_max_f32_e32 v163, v163, v163
	v_max_f32_e32 v162, v162, v162
	v_max_f32_e32 v162, v162, v163
	v_cmp_lt_f32_e32 vcc, v234, v162
	s_cbranch_vccz .LBB0_125
; DI float fexp2(float x) { return __builtin_amdgcn_exp2f(x); }
; template <int MODE>
; DI void attn_tile(const Params& p, int layer, int tile, char* smem) {
;     ...
;       if (__any(fresh || (started && mt > 8.f))) {
;         float delta = 0.f, al = 1.f;
;         if (fresh) { delta = mt; started = true; }
;         else if (started) { delta = __builtin_fmaxf(mt, 0.f); al = fexp2(-delta); }
;         mref += delta;
;         lsum *= al;
; #pragma unroll
;         for (int i = 0; i < 16; ++i) { o0[i] *= al; o1[i] *= al; s0[i] -= delta; s1[i] -= delta; negm[i] = -mref; }
;       }
	v_and_b32_e32 v163, 1, v211
	v_cmp_eq_u32_e64 s[12:13], 1, v163
	v_cmp_nlt_f32_e64 s[10:11], s33, v162
	s_nop 0
	v_max_f32_e32 v34, v162, v162
	v_max_f32_e32 v34, 0, v34
	v_exp_f32_e64 v35, -v34
	v_cndmask_b32_e64 v36, v162, 0, s[10:11]
	v_cndmask_b32_e64 v36, v36, v34, s[12:13]
	v_add_f32_e32 v210, v210, v36
	s_or_b64 vcc, s[10:11], s[12:13]
	v_cndmask_b32_e64 v38, 1.0, v35, s[12:13]
	v_xor_b32_e32 v34, 0x80000000, v210
	v_cndmask_b32_e32 v211, 1, v211, vcc
	v_and_b32_e32 v235, 1, v211
	v_cmp_eq_u32_e32 vcc, 1, v235
	v_mov_b32_e32 v235, 0x41000000
	v_mov_b32_e32 v236, 0xefa18f08
	v_cndmask_b32_e32 v234, v236, v235, vcc
	v_mul_f32_e32 v0, v0, v38
	v_pk_add_f32 v[66:67], v[66:67], v[36:37] op_sel_hi:[1,0] neg_lo:[0,1] neg_hi:[0,1]
	v_pk_add_f32 v[50:51], v[50:51], v[36:37] op_sel_hi:[1,0] neg_lo:[0,1] neg_hi:[0,1]
	v_pk_add_f32 v[68:69], v[68:69], v[36:37] op_sel_hi:[1,0] neg_lo:[0,1] neg_hi:[0,1]
	v_pk_add_f32 v[52:53], v[52:53], v[36:37] op_sel_hi:[1,0] neg_lo:[0,1] neg_hi:[0,1]
	v_pk_add_f32 v[70:71], v[70:71], v[36:37] op_sel_hi:[1,0] neg_lo:[0,1] neg_hi:[0,1]
	v_pk_add_f32 v[54:55], v[54:55], v[36:37] op_sel_hi:[1,0] neg_lo:[0,1] neg_hi:[0,1]
	v_pk_add_f32 v[72:73], v[72:73], v[36:37] op_sel_hi:[1,0] neg_lo:[0,1] neg_hi:[0,1]
	v_pk_add_f32 v[56:57], v[56:57], v[36:37] op_sel_hi:[1,0] neg_lo:[0,1] neg_hi:[0,1]
	v_pk_add_f32 v[74:75], v[74:75], v[36:37] op_sel_hi:[1,0] neg_lo:[0,1] neg_hi:[0,1]
	v_pk_add_f32 v[58:59], v[58:59], v[36:37] op_sel_hi:[1,0] neg_lo:[0,1] neg_hi:[0,1]
	v_pk_add_f32 v[76:77], v[76:77], v[36:37] op_sel_hi:[1,0] neg_lo:[0,1] neg_hi:[0,1]
	v_pk_add_f32 v[60:61], v[60:61], v[36:37] op_sel_hi:[1,0] neg_lo:[0,1] neg_hi:[0,1]
	v_pk_add_f32 v[78:79], v[78:79], v[36:37] op_sel_hi:[1,0] neg_lo:[0,1] neg_hi:[0,1]
	v_pk_add_f32 v[62:63], v[62:63], v[36:37] op_sel_hi:[1,0] neg_lo:[0,1] neg_hi:[0,1]
	v_pk_mul_f32 v[32:33], v[32:33], v[38:39] op_sel_hi:[1,0]
	v_pk_mul_f32 v[30:31], v[30:31], v[38:39] op_sel_hi:[1,0]
	v_pk_mul_f32 v[28:29], v[28:29], v[38:39] op_sel_hi:[1,0]
	v_pk_mul_f32 v[26:27], v[26:27], v[38:39] op_sel_hi:[1,0]
	v_pk_mul_f32 v[24:25], v[24:25], v[38:39] op_sel_hi:[1,0]
	v_pk_mul_f32 v[22:23], v[22:23], v[38:39] op_sel_hi:[1,0]
	v_pk_mul_f32 v[20:21], v[20:21], v[38:39] op_sel_hi:[1,0]
	v_pk_mul_f32 v[18:19], v[18:19], v[38:39] op_sel_hi:[1,0]
	v_pk_mul_f32 v[16:17], v[16:17], v[38:39] op_sel_hi:[1,0]
	v_pk_mul_f32 v[14:15], v[14:15], v[38:39] op_sel_hi:[1,0]
	v_pk_mul_f32 v[12:13], v[12:13], v[38:39] op_sel_hi:[1,0]
	v_pk_mul_f32 v[10:11], v[10:11], v[38:39] op_sel_hi:[1,0]
	v_pk_mul_f32 v[8:9], v[8:9], v[38:39] op_sel_hi:[1,0]
	v_pk_mul_f32 v[6:7], v[6:7], v[38:39] op_sel_hi:[1,0]
	v_pk_mul_f32 v[4:5], v[4:5], v[38:39] op_sel_hi:[1,0]
	v_pk_mul_f32 v[2:3], v[2:3], v[38:39] op_sel_hi:[1,0]
	v_pk_add_f32 v[80:81], v[80:81], v[36:37] op_sel_hi:[1,0] neg_lo:[0,1] neg_hi:[0,1]
	v_pk_add_f32 v[64:65], v[64:65], v[36:37] op_sel_hi:[1,0] neg_lo:[0,1] neg_hi:[0,1]
	v_mov_b32_e32 v35, v34
	v_mov_b32_e32 v36, v34
	v_mov_b32_e32 v37, v34
	v_mov_b32_e32 v38, v34
	v_mov_b32_e32 v39, v34
	v_mov_b32_e32 v40, v34
	v_mov_b32_e32 v41, v34
	v_mov_b32_e32 v42, v34
	v_mov_b32_e32 v43, v34
	v_mov_b32_e32 v44, v34
	v_mov_b32_e32 v45, v34
	v_mov_b32_e32 v46, v34
	v_mov_b32_e32 v47, v34
	v_mov_b32_e32 v48, v34
	v_mov_b32_e32 v49, v34
